# the one cooperative-groups grid sync (after the independent start phases) also goes through the XCD barrier
# baseline (speedup 1.0000x reference)
.LBB0_517:
	s_cmp_lt_i32 s24, 2
	s_cselect_b64 s[0:1], -1, 0
	s_xor_b64 s[6:7], s[6:7], -1
	s_or_b64 s[0:1], s[0:1], s[6:7]
	s_and_b64 vcc, exec, s[0:1]
	s_cbranch_vccnz .LBB0_5
	s_cmp_lg_u32 s24, 2
	s_mov_b64 s[6:7], -1
	s_waitcnt vmcnt(0) lgkmcnt(0)
	v_readlane_b32 s28, v254, 41
	v_readlane_b32 s29, v254, 42
	v_readlane_b32 s0, v254, 28
	s_load_dwordx2 s[28:29], s[28:29], 0x120
	s_add_i32 s13, s0, 1
	s_waitcnt vmcnt(0)
	s_barrier
	s_mov_b64 s[6:7], exec
	v_readlane_b32 s0, v254, 29
	v_readlane_b32 s1, v254, 30
	s_and_b64 s[0:1], s[6:7], s[0:1]
	s_mov_b64 exec, s[0:1]
	s_cbranch_execz .LBB0_525
	s_getreg_b32 s8, hwreg(HW_REG_XCC_ID, 0, 4)
	s_and_b32 s8, s8, 7
	s_lshr_b32 s9, s54, 3
	v_mov_b32_e32 v1, 1
	s_mul_i32 s9, s9, s13
	s_lshl_b32 s11, s8, 4
	s_lshl_b32 s18, s8, 3
	s_add_u32 s18, s18, 0x80
	v_mov_b32_e32 v3, s11
	v_mov_b32_e32 v5, s18
	s_waitcnt lgkmcnt(0)
	s_add_u32 s0, s28, 0x198000
	s_addc_u32 s1, s29, 0
	global_atomic_add v3, v3, v1, s[0:1] sc0
	buffer_inv sc1
	s_mov_b32 s20, 0
	s_lshl_b32 s21, s13, 3
	s_waitcnt vmcnt(1)
	v_add_u32_e32 v3, 1, v3
	v_cmp_eq_u32_e32 vcc, s9, v3
	s_cbranch_vccz .Lxb_early
	buffer_wbl2 sc1
	s_waitcnt vmcnt(0)
	global_atomic_add v3, v2, v1, s[0:1] offset:192 sc0
	s_waitcnt vmcnt(0)
	v_add_u32_e32 v3, 1, v3
	v_cmp_eq_u32_e32 vcc, s21, v3
	s_cbranch_vccz .Lxb_fspin
	global_atomic_add v2, v1, s[0:1] offset:128
	global_atomic_add v2, v1, s[0:1] offset:136
	global_atomic_add v2, v1, s[0:1] offset:144
	global_atomic_add v2, v1, s[0:1] offset:152
	global_atomic_add v2, v1, s[0:1] offset:160
	global_atomic_add v2, v1, s[0:1] offset:168
	global_atomic_add v2, v1, s[0:1] offset:176
	global_atomic_add v2, v1, s[0:1] offset:184
	s_branch .Lxb_done
